# v11 + Swiglu epilogue caches the 8 per-lane row rstd values in registers across consecutive tiles with the same row block (skips the row-stat loads and reduction when unchanged)
# speedup vs baseline: 1.0236x; 1.0205x over previous
_Z8yoco_fwd6Params:
	s_mov_b32 s98, -1
	s_load_dwordx2 s[90:91], s[0:1], 0xd0
	s_load_dwordx4 s[4:7], s[0:1], 0xc0
	s_mov_b32 s88, s2
	s_load_dword s2, s[0:1], 0xe8
	v_and_b32_e32 v184, 0x3ff, v0
	s_waitcnt lgkmcnt(0)
	v_writelane_b32 v254, s4, 0
	s_nop 1
	v_writelane_b32 v254, s5, 1
	v_writelane_b32 v254, s6, 2
	v_writelane_b32 v254, s7, 3
	v_writelane_b32 v254, s2, 4
	s_load_dwordx2 s[2:3], s[0:1], 0xe0
	s_add_u32 s6, s0, 0xe0
	s_addc_u32 s7, s1, 0
	s_add_u32 s92, s90, 0xb700000
	s_addc_u32 s93, s91, 0
	s_waitcnt lgkmcnt(0)
	v_writelane_b32 v254, s2, 5
	s_cmp_lg_u32 s88, 0
	s_nop 0
	v_writelane_b32 v254, s3, 6
	s_mov_b32 s2, 0
	s_cbranch_scc1 .LBB0_8
	v_sub_u32_e32 v1, 0xd7f, v184
	v_lshrrev_b32_e32 v2, 9, v1
	v_add_u32_e32 v1, 2, v2
	v_add_u32_e32 v185, 0x200, v184
	v_and_b32_e32 v3, 14, v1
	v_mov_b32_e32 v1, v2
	s_mov_b64 s[8:9], 0
	s_mov_b32 s3, 1
	v_mov_b32_e32 v5, 0
	s_mov_b32 s10, s2
	v_mov_b64_e32 v[6:7], v[184:185]
	s_branch .LBB0_3

.LBB0_635:
	s_mov_b32 s99, s0
	s_cmp_eq_u32 s99, s98
	s_cbranch_scc1 .Lsw_skip_a
	s_mov_b32 s98, s99
	v_mov_b32_e32 v128, v172
	v_mov_b32_e32 v129, v173
	s_lshl_b32 s0, s0, 8
	s_add_i32 s0, s0, s36
	v_lshlrev_b32_e32 v144, 3, v129
	v_add_u32_e32 v181, s0, v128
	v_ashrrev_i32_e32 v145, 31, v144
	v_lshlrev_b32_e32 v160, 5, v181
	v_lshl_add_u64 v[182:183], v[144:145], 2, s[76:77]
	v_lshl_add_u64 v[132:133], v[160:161], 2, v[182:183]
	v_add_u32_e32 v136, 0x200, v160
	v_mov_b32_e32 v137, v161
	global_load_dwordx4 v[128:131], v[132:133], off
	s_nop 0
	global_load_dwordx4 v[132:135], v[132:133], off offset:16
	v_lshl_add_u64 v[140:141], v[136:137], 2, v[182:183]
	global_load_dwordx4 v[136:139], v[140:141], off
	s_nop 0
	global_load_dwordx4 v[140:143], v[140:141], off offset:16
	v_and_b32_e32 v148, 64, v178
	s_lshl_b32 s0, s1, 7
	v_xor_b32_e32 v146, 16, v178
	v_add_u32_e32 v148, 64, v148
	s_or_b32 s0, s0, s37
	v_cmp_lt_i32_e32 vcc, v146, v148
	v_mov_b32_e32 v145, v161
	v_add_u32_e32 v170, s0, v144
	v_cndmask_b32_e32 v146, v178, v146, vcc
	v_add_u32_e32 v144, 0x400, v160
	v_mov_b32_e32 v147, v161
	v_mov_b32_e32 v187, v161
	v_lshlrev_b32_e32 v171, 2, v146
	v_add_u32_e32 v146, 0x600, v160
	v_add_u32_e32 v186, 0x1400, v160
	v_lshl_add_u64 v[144:145], v[144:145], 2, v[182:183]
	v_lshl_add_u64 v[146:147], v[146:147], 2, v[182:183]
	v_lshl_add_u64 v[212:213], v[186:187], 2, v[182:183]
	global_load_dwordx4 v[186:189], v[144:145], off
	global_load_dwordx4 v[190:193], v[144:145], off offset:16
	global_load_dwordx4 v[194:197], v[146:147], off
	global_load_dwordx4 v[198:201], v[146:147], off offset:16
	v_xor_b32_e32 v150, 32, v178
	v_cmp_lt_i32_e32 vcc, v150, v148
	v_mov_b32_e32 v149, v161
	v_mov_b32_e32 v151, v161
	v_cndmask_b32_e32 v148, v178, v150, vcc
	v_lshlrev_b32_e32 v214, 2, v148
	v_add_u32_e32 v148, 0x1000, v160
	v_add_u32_e32 v150, 0x1200, v160
	v_add_u32_e32 v160, 0x1600, v160
	v_lshl_add_u64 v[148:149], v[148:149], 2, v[182:183]
	v_lshl_add_u64 v[210:211], v[150:151], 2, v[182:183]
	global_load_dwordx4 v[220:223], v[148:149], off
	global_load_dwordx4 v[224:227], v[148:149], off offset:16
	global_load_dwordx4 v[228:231], v[210:211], off
	global_load_dwordx4 v[232:235], v[210:211], off offset:16
	global_load_dwordx4 v[236:239], v[212:213], off
	global_load_dwordx4 v[240:243], v[212:213], off offset:16
	v_pk_mul_f32 v[122:123], v[126:127], v[122:123]
	v_pk_mul_f32 v[120:121], v[124:125], v[120:121]
	v_pk_mul_f32 v[112:113], v[116:117], v[112:113]
	v_pk_mul_f32 v[114:115], v[118:119], v[114:115]
	v_pk_mul_f32 v[106:107], v[110:111], v[106:107]
	v_pk_mul_f32 v[104:105], v[108:109], v[104:105]
	v_pk_mul_f32 v[98:99], v[102:103], v[98:99]
	v_pk_mul_f32 v[96:97], v[100:101], v[96:97]
	v_pk_mul_f32 v[90:91], v[94:95], v[90:91]
	v_pk_mul_f32 v[88:89], v[92:93], v[88:89]
	v_pk_mul_f32 v[82:83], v[86:87], v[82:83]
	v_pk_mul_f32 v[80:81], v[84:85], v[80:81]
	v_pk_mul_f32 v[74:75], v[78:79], v[74:75]
	v_pk_mul_f32 v[72:73], v[76:77], v[72:73]
	v_pk_mul_f32 v[66:67], v[70:71], v[66:67]
	v_pk_mul_f32 v[64:65], v[68:69], v[64:65]
	v_pk_mul_f32 v[58:59], v[62:63], v[58:59]
	v_pk_mul_f32 v[56:57], v[60:61], v[56:57]
	v_pk_mul_f32 v[50:51], v[54:55], v[50:51]
	v_pk_mul_f32 v[48:49], v[52:53], v[48:49]
	v_pk_mul_f32 v[42:43], v[46:47], v[42:43]
	v_pk_mul_f32 v[40:41], v[44:45], v[40:41]
	v_pk_mul_f32 v[34:35], v[38:39], v[34:35]
	v_pk_mul_f32 v[32:33], v[36:37], v[32:33]
	v_pk_mul_f32 v[26:27], v[30:31], v[26:27]
	v_pk_mul_f32 v[24:25], v[28:29], v[24:25]
	v_pk_mul_f32 v[18:19], v[22:23], v[18:19]
	v_pk_mul_f32 v[16:17], v[20:21], v[16:17]
	v_pk_mul_f32 v[10:11], v[14:15], v[10:11]
	v_pk_mul_f32 v[8:9], v[12:13], v[8:9]
	v_pk_mul_f32 v[2:3], v[6:7], v[2:3]
	v_pk_mul_f32 v[0:1], v[4:5], v[0:1]
	s_waitcnt vmcnt(0)
	v_mov_b32_e32 v144, v128
	v_mov_b32_e32 v145, v132
	v_mov_b32_e32 v132, v129
	v_mov_b32_e32 v128, v130
	v_mov_b32_e32 v129, v134
	v_mov_b32_e32 v134, v131
	v_mov_b32_e32 v130, v136
	v_mov_b32_e32 v131, v140
	v_mov_b32_e32 v140, v137
	v_mov_b32_e32 v136, v138
	v_mov_b32_e32 v137, v142
	v_mov_b32_e32 v142, v139
	v_pk_add_f32 v[132:133], v[144:145], v[132:133]
	v_pk_add_f32 v[128:129], v[128:129], v[134:135]
	v_pk_add_f32 v[130:131], v[130:131], v[140:141]
	v_pk_add_f32 v[134:135], v[136:137], v[142:143]
	v_pk_add_f32 v[128:129], v[132:133], v[128:129]
	v_pk_add_f32 v[130:131], v[130:131], v[134:135]
	v_add_f32_e32 v128, v128, v129
	v_add_f32_e32 v129, v130, v131
	s_nop 0
	s_waitcnt lgkmcnt(0)
	v_mov_b32_e32 v130, v128
	v_mov_b32_e32 v253, v128
	s_nop 1
	v_permlane16_swap_b32_e32 v130, v253
	v_add_f32_e32 v130, v130, v253
	s_waitcnt lgkmcnt(0)
	v_mov_b32_e32 v131, v129
	v_mov_b32_e32 v253, v129
	s_nop 1
	v_permlane16_swap_b32_e32 v131, v253
	v_add_f32_e32 v131, v131, v253
	v_lshl_add_u64 v[128:129], v[160:161], 2, v[182:183]
	s_waitcnt lgkmcnt(0)
	v_mov_b32_e32 v132, v130
	v_mov_b32_e32 v253, v130
	s_nop 1
	v_permlane32_swap_b32_e32 v132, v253
	v_add_f32_e32 v130, v132, v253
	v_fmamk_f32 v130, v130, 0x3a000000, v179
	v_rsq_f32_e32 v202, v130
	s_waitcnt lgkmcnt(0)
	v_mov_b32_e32 v133, v131
	v_mov_b32_e32 v253, v131
	s_nop 1
	v_permlane32_swap_b32_e32 v133, v253
	v_add_f32_e32 v131, v133, v253
	v_fmamk_f32 v131, v131, 0x3a000000, v179
	v_rsq_f32_e32 v203, v131
	global_load_dwordx4 v[132:135], v[128:129], off
	s_nop 0
	global_load_dwordx4 v[128:131], v[128:129], off offset:16
	v_mov_b32_e32 v182, v186
	v_mov_b32_e32 v183, v190
	v_mov_b32_e32 v190, v187
	v_mov_b32_e32 v186, v188
	v_mov_b32_e32 v187, v192
	v_mov_b32_e32 v192, v189
	v_pk_add_f32 v[182:183], v[182:183], v[190:191]
	v_pk_add_f32 v[186:187], v[186:187], v[192:193]
	v_pk_add_f32 v[182:183], v[182:183], v[186:187]
	v_add_f32_e32 v182, v182, v183
	v_mov_b32_e32 v160, v202
	v_mov_b32_e32 v244, v202
	s_waitcnt lgkmcnt(0)
	v_mov_b32_e32 v183, v182
	v_mov_b32_e32 v253, v182
	s_nop 1
	v_permlane16_swap_b32_e32 v183, v253
	v_add_f32_e32 v182, v183, v253
	s_waitcnt lgkmcnt(0)
	v_mov_b32_e32 v183, v182
	v_mov_b32_e32 v253, v182
	s_nop 1
	v_permlane32_swap_b32_e32 v183, v253
	v_add_f32_e32 v182, v183, v253
	v_fmamk_f32 v182, v182, 0x3a000000, v179
	v_rsq_f32_e32 v204, v182
	v_mov_b32_e32 v186, v196
	v_mov_b32_e32 v187, v200
	v_mov_b32_e32 v182, v194
	v_mov_b32_e32 v183, v198
	v_mov_b32_e32 v198, v195
	v_mov_b32_e32 v200, v197
	v_pk_add_f32 v[182:183], v[182:183], v[198:199]
	v_pk_add_f32 v[186:187], v[186:187], v[200:201]
	v_pk_add_f32 v[182:183], v[182:183], v[186:187]
	v_add_f32_e32 v182, v182, v183
	v_mov_b32_e32 v188, v203
	v_mov_b32_e32 v245, v203
	s_waitcnt lgkmcnt(0)
	v_mov_b32_e32 v183, v182
	v_mov_b32_e32 v253, v182
	s_nop 1
	v_permlane16_swap_b32_e32 v183, v253
	v_add_f32_e32 v182, v183, v253
	s_waitcnt lgkmcnt(0)
	v_mov_b32_e32 v183, v182
	v_mov_b32_e32 v253, v182
	s_nop 1
	v_permlane32_swap_b32_e32 v183, v253
	v_add_f32_e32 v182, v183, v253
	v_fmamk_f32 v182, v182, 0x3a000000, v179
	v_rsq_f32_e32 v205, v182
	s_waitcnt vmcnt(7)
	v_mov_b32_e32 v186, v222
	s_waitcnt vmcnt(6)
	v_mov_b32_e32 v187, v226
	v_mov_b32_e32 v182, v220
	v_mov_b32_e32 v183, v224
	v_mov_b32_e32 v224, v221
	v_mov_b32_e32 v226, v223
	v_pk_add_f32 v[182:183], v[182:183], v[224:225]
	v_pk_add_f32 v[186:187], v[186:187], v[226:227]
	v_pk_add_f32 v[182:183], v[182:183], v[186:187]
	v_add_f32_e32 v182, v182, v183
	s_waitcnt lgkmcnt(0)
	v_mov_b32_e32 v183, v182
	v_mov_b32_e32 v253, v182
	s_nop 1
	v_permlane16_swap_b32_e32 v183, v253
	v_add_f32_e32 v182, v183, v253
	v_mov_b32_e32 v186, v204
	v_mov_b32_e32 v246, v204
	s_waitcnt lgkmcnt(0)
	v_mov_b32_e32 v183, v182
	v_mov_b32_e32 v253, v182
	s_nop 1
	v_permlane32_swap_b32_e32 v183, v253
	v_add_f32_e32 v182, v183, v253
	v_fmamk_f32 v182, v182, 0x3a000000, v179
	v_rsq_f32_e32 v206, v182
	s_waitcnt vmcnt(5)
	v_mov_b32_e32 v182, v228
	s_waitcnt vmcnt(4)
	v_mov_b32_e32 v183, v232
	v_mov_b32_e32 v232, v229
	v_mov_b32_e32 v228, v230
	v_mov_b32_e32 v229, v234
	v_mov_b32_e32 v234, v231
	v_pk_add_f32 v[232:233], v[182:183], v[232:233]
	v_pk_add_f32 v[234:235], v[228:229], v[234:235]
	v_pk_add_f32 v[232:233], v[232:233], v[234:235]
	v_add_f32_e32 v232, v232, v233
	s_waitcnt lgkmcnt(0)
	v_mov_b32_e32 v233, v232
	v_mov_b32_e32 v253, v232
	s_nop 1
	v_permlane16_swap_b32_e32 v233, v253
	v_add_f32_e32 v232, v233, v253
	s_waitcnt lgkmcnt(0)
	v_mov_b32_e32 v233, v232
	v_mov_b32_e32 v253, v232
	s_nop 1
	v_permlane32_swap_b32_e32 v233, v253
	v_add_f32_e32 v232, v233, v253
	v_fmamk_f32 v232, v232, 0x3a000000, v179
	v_rsq_f32_e32 v207, v232
	v_mov_b32_e32 v234, v205
	v_mov_b32_e32 v247, v205
	s_waitcnt vmcnt(3)
	v_mov_b32_e32 v232, v236
	s_waitcnt vmcnt(2)
	v_mov_b32_e32 v233, v240
	v_mov_b32_e32 v240, v237
	v_mov_b32_e32 v236, v238
	v_mov_b32_e32 v237, v242
	v_mov_b32_e32 v242, v239
	v_pk_add_f32 v[240:241], v[232:233], v[240:241]
	v_pk_add_f32 v[242:243], v[236:237], v[242:243]
	v_pk_add_f32 v[240:241], v[240:241], v[242:243]
	v_add_f32_e32 v240, v240, v241
	s_waitcnt lgkmcnt(0)
	v_mov_b32_e32 v241, v240
	v_mov_b32_e32 v253, v240
	s_nop 1
	v_permlane16_swap_b32_e32 v241, v253
	v_add_f32_e32 v240, v241, v253
	s_waitcnt lgkmcnt(0)
	v_mov_b32_e32 v241, v240
	v_mov_b32_e32 v253, v240
	s_nop 1
	v_permlane32_swap_b32_e32 v241, v253
	v_add_f32_e32 v240, v241, v253
	v_fmamk_f32 v240, v240, 0x3a000000, v179
	v_rsq_f32_e32 v208, v240
	v_mov_b32_e32 v242, v206
	v_mov_b32_e32 v248, v206
	s_waitcnt vmcnt(1)
	v_mov_b32_e32 v240, v132
	s_waitcnt vmcnt(0)
	v_mov_b32_e32 v241, v128
	v_mov_b32_e32 v128, v133
	v_mov_b32_e32 v132, v134
	v_mov_b32_e32 v133, v130
	v_mov_b32_e32 v130, v135
	v_pk_add_f32 v[128:129], v[240:241], v[128:129]
	v_pk_add_f32 v[130:131], v[132:133], v[130:131]
	v_pk_add_f32 v[128:129], v[128:129], v[130:131]
	v_add_f32_e32 v128, v128, v129
	v_mov_b32_e32 v131, v207
	v_mov_b32_e32 v249, v207
	s_waitcnt lgkmcnt(0)
	v_mov_b32_e32 v129, v128
	v_mov_b32_e32 v253, v128
	s_nop 1
	v_permlane16_swap_b32_e32 v129, v253
	v_add_f32_e32 v128, v129, v253
	s_waitcnt lgkmcnt(0)
	v_mov_b32_e32 v129, v128
	v_mov_b32_e32 v253, v128
	s_nop 1
	v_permlane32_swap_b32_e32 v129, v253
	v_add_f32_e32 v128, v129, v253
	v_fmamk_f32 v128, v128, 0x3a000000, v179
	v_rsq_f32_e32 v209, v128
	v_mov_b32_e32 v243, v208
	v_mov_b32_e32 v250, v208
	v_ashrrev_i32_e32 v171, 31, v170
	v_mul_f32_e32 v130, 0xbfb8aa3b, v160
	v_pk_mul_f32 v[240:241], v[124:125], v[130:131] op_sel_hi:[1,0]
	v_mov_b32_e32 v128, v209
	v_mov_b32_e32 v251, v209
	s_branch .Lsw_join_a
.Lsw_skip_a:
	v_mov_b32_e32 v128, v172
	v_mov_b32_e32 v129, v173
	s_lshl_b32 s0, s0, 8
	s_add_i32 s0, s0, s36
	v_lshlrev_b32_e32 v144, 3, v129
	v_add_u32_e32 v181, s0, v128
	v_ashrrev_i32_e32 v145, 31, v144
	v_lshlrev_b32_e32 v160, 5, v181
	v_lshl_add_u64 v[182:183], v[144:145], 2, s[76:77]
	v_lshl_add_u64 v[132:133], v[160:161], 2, v[182:183]
	v_add_u32_e32 v136, 0x200, v160
	v_mov_b32_e32 v137, v161
	v_lshl_add_u64 v[140:141], v[136:137], 2, v[182:183]
	v_and_b32_e32 v148, 64, v178
	s_lshl_b32 s0, s1, 7
	v_xor_b32_e32 v146, 16, v178
	v_add_u32_e32 v148, 64, v148
	s_or_b32 s0, s0, s37
	v_cmp_lt_i32_e32 vcc, v146, v148
	v_mov_b32_e32 v145, v161
	v_add_u32_e32 v170, s0, v144
	v_cndmask_b32_e32 v146, v178, v146, vcc
	v_add_u32_e32 v144, 0x400, v160
	v_mov_b32_e32 v147, v161
	v_mov_b32_e32 v187, v161
	v_lshlrev_b32_e32 v171, 2, v146
	v_add_u32_e32 v146, 0x600, v160
	v_add_u32_e32 v186, 0x1400, v160
	v_lshl_add_u64 v[144:145], v[144:145], 2, v[182:183]
	v_lshl_add_u64 v[146:147], v[146:147], 2, v[182:183]
	v_lshl_add_u64 v[212:213], v[186:187], 2, v[182:183]
	v_xor_b32_e32 v150, 32, v178
	v_cmp_lt_i32_e32 vcc, v150, v148
	v_mov_b32_e32 v149, v161
	v_mov_b32_e32 v151, v161
	v_cndmask_b32_e32 v148, v178, v150, vcc
	v_lshlrev_b32_e32 v214, 2, v148
	v_add_u32_e32 v148, 0x1000, v160
	v_add_u32_e32 v150, 0x1200, v160
	v_add_u32_e32 v160, 0x1600, v160
	v_lshl_add_u64 v[148:149], v[148:149], 2, v[182:183]
	v_lshl_add_u64 v[210:211], v[150:151], 2, v[182:183]
	v_pk_mul_f32 v[122:123], v[126:127], v[122:123]
	v_pk_mul_f32 v[120:121], v[124:125], v[120:121]
	v_pk_mul_f32 v[112:113], v[116:117], v[112:113]
	v_pk_mul_f32 v[114:115], v[118:119], v[114:115]
	v_pk_mul_f32 v[106:107], v[110:111], v[106:107]
	v_pk_mul_f32 v[104:105], v[108:109], v[104:105]
	v_pk_mul_f32 v[98:99], v[102:103], v[98:99]
	v_pk_mul_f32 v[96:97], v[100:101], v[96:97]
	v_pk_mul_f32 v[90:91], v[94:95], v[90:91]
	v_pk_mul_f32 v[88:89], v[92:93], v[88:89]
	v_pk_mul_f32 v[82:83], v[86:87], v[82:83]
	v_pk_mul_f32 v[80:81], v[84:85], v[80:81]
	v_pk_mul_f32 v[74:75], v[78:79], v[74:75]
	v_pk_mul_f32 v[72:73], v[76:77], v[72:73]
	v_pk_mul_f32 v[66:67], v[70:71], v[66:67]
	v_pk_mul_f32 v[64:65], v[68:69], v[64:65]
	v_pk_mul_f32 v[58:59], v[62:63], v[58:59]
	v_pk_mul_f32 v[56:57], v[60:61], v[56:57]
	v_pk_mul_f32 v[50:51], v[54:55], v[50:51]
	v_pk_mul_f32 v[48:49], v[52:53], v[48:49]
	v_pk_mul_f32 v[42:43], v[46:47], v[42:43]
	v_pk_mul_f32 v[40:41], v[44:45], v[40:41]
	v_pk_mul_f32 v[34:35], v[38:39], v[34:35]
	v_pk_mul_f32 v[32:33], v[36:37], v[32:33]
	v_pk_mul_f32 v[26:27], v[30:31], v[26:27]
	v_pk_mul_f32 v[24:25], v[28:29], v[24:25]
	v_pk_mul_f32 v[18:19], v[22:23], v[18:19]
	v_pk_mul_f32 v[16:17], v[20:21], v[16:17]
	v_pk_mul_f32 v[10:11], v[14:15], v[10:11]
	v_pk_mul_f32 v[8:9], v[12:13], v[8:9]
	v_pk_mul_f32 v[2:3], v[6:7], v[2:3]
	v_pk_mul_f32 v[0:1], v[4:5], v[0:1]
	v_lshl_add_u64 v[128:129], v[160:161], 2, v[182:183]
	v_mov_b32_e32 v160, v244
	v_mov_b32_e32 v188, v245
	v_mov_b32_e32 v186, v246
	v_mov_b32_e32 v234, v247
	v_mov_b32_e32 v242, v248
	v_mov_b32_e32 v131, v249
	v_mov_b32_e32 v243, v250
	v_ashrrev_i32_e32 v171, 31, v170
	v_mul_f32_e32 v130, 0xbfb8aa3b, v160
	v_pk_mul_f32 v[240:241], v[124:125], v[130:131] op_sel_hi:[1,0]
	v_mov_b32_e32 v128, v251
.Lsw_join_a:
	v_exp_f32_e32 v129, v240
	v_pk_mul_f32 v[134:135], v[126:127], v[130:131] op_sel_hi:[1,0]
	v_exp_f32_e32 v133, v241
	v_exp_f32_e32 v240, v134
	v_exp_f32_e32 v241, v135
	v_add_f32_e32 v129, 1.0, v129
	v_rcp_f32_e32 v134, v129
	v_add_f32_e32 v129, 1.0, v133
	v_rcp_f32_e32 v135, v129
	v_add_f32_e32 v129, 1.0, v240
	v_pk_mul_f32 v[126:127], v[116:117], v[130:131] op_sel_hi:[1,0]
	v_rcp_f32_e32 v240, v129
	v_add_f32_e32 v129, 1.0, v241
	v_pk_mul_f32 v[124:125], v[118:119], v[130:131] op_sel_hi:[1,0]
	v_exp_f32_e32 v126, v126
	v_exp_f32_e32 v127, v127
	v_rcp_f32_e32 v241, v129
	v_exp_f32_e32 v129, v124
	v_exp_f32_e32 v130, v125
	v_add_f32_e32 v124, 1.0, v126
	v_add_f32_e32 v125, 1.0, v127
	v_rcp_f32_e32 v124, v124
	v_rcp_f32_e32 v125, v125
	v_add_f32_e32 v126, 1.0, v129
	v_add_f32_e32 v127, 1.0, v130
	v_rcp_f32_e32 v126, v126
	v_rcp_f32_e32 v127, v127
	v_mul_f32_e32 v132, v160, v160
	v_pk_mul_f32 v[112:113], v[112:113], v[132:133] op_sel_hi:[1,0]
	v_pk_mul_f32 v[120:121], v[120:121], v[132:133] op_sel_hi:[1,0]
	v_pk_mul_f32 v[122:123], v[122:123], v[132:133] op_sel_hi:[1,0]
	v_pk_mul_f32 v[114:115], v[114:115], v[132:133] op_sel_hi:[1,0]
	v_pk_mul_f32 v[112:113], v[112:113], v[124:125]
	v_pk_mul_f32 v[122:123], v[122:123], v[240:241]
	v_pk_mul_f32 v[120:121], v[120:121], v[134:135]
	v_pk_mul_f32 v[114:115], v[114:115], v[126:127]
	v_cvt_pk_bf16_f32 v116, v120, v121
	v_cvt_pk_bf16_f32 v117, v122, v123
	v_cvt_pk_bf16_f32 v118, v112, v113
	v_mov_b64_e32 v[112:113], s[68:69]
	v_cvt_pk_bf16_f32 v119, v114, v115
	v_mad_i64_i32 v[120:121], s[0:1], v181, s45, v[112:113]
	v_lshlrev_b64 v[114:115], 1, v[170:171]
	v_lshl_add_u64 v[120:121], v[120:121], 0, v[114:115]
	global_store_dwordx4 v[120:121], v[116:119], off
	s_andn2_b64 vcc, exec, s[4:5]
	s_nop 0
	v_mul_f32_e32 v116, 0xbfb8aa3b, v188
	v_pk_mul_f32 v[122:123], v[108:109], v[116:117] op_sel_hi:[1,0]
	v_pk_mul_f32 v[120:121], v[110:111], v[116:117] op_sel_hi:[1,0]
	v_exp_f32_e32 v117, v122
	v_exp_f32_e32 v119, v123
	v_exp_f32_e32 v122, v120
	v_exp_f32_e32 v123, v121
	v_add_f32_e32 v117, 1.0, v117
	v_rcp_f32_e32 v120, v117
	v_add_f32_e32 v117, 1.0, v119
	v_rcp_f32_e32 v121, v117
	v_add_f32_e32 v117, 1.0, v122
	v_rcp_f32_e32 v122, v117
	v_add_f32_e32 v117, 1.0, v123
	v_pk_mul_f32 v[108:109], v[102:103], v[116:117] op_sel_hi:[1,0]
	v_pk_mul_f32 v[110:111], v[100:101], v[116:117] op_sel_hi:[1,0]
	v_rcp_f32_e32 v123, v117
	v_exp_f32_e32 v110, v110
	v_exp_f32_e32 v111, v111
	v_exp_f32_e32 v116, v108
	v_exp_f32_e32 v117, v109
	v_add_f32_e32 v108, 1.0, v110
	v_add_f32_e32 v109, 1.0, v111
	v_add_f32_e32 v110, 1.0, v116
	v_add_f32_e32 v111, 1.0, v117
	v_rcp_f32_e32 v108, v108
	v_rcp_f32_e32 v109, v109
	v_rcp_f32_e32 v110, v110
	v_rcp_f32_e32 v111, v111
	v_mul_f32_e32 v118, v188, v188
	v_pk_mul_f32 v[96:97], v[96:97], v[118:119] op_sel_hi:[1,0]
	v_pk_mul_f32 v[98:99], v[98:99], v[118:119] op_sel_hi:[1,0]
	v_pk_mul_f32 v[104:105], v[104:105], v[118:119] op_sel_hi:[1,0]
	v_pk_mul_f32 v[106:107], v[106:107], v[118:119] op_sel_hi:[1,0]
	v_pk_mul_f32 v[100:101], v[98:99], v[110:111]
	v_pk_mul_f32 v[98:99], v[96:97], v[108:109]
	v_add_u32_e32 v102, 16, v181
	v_pk_mul_f32 v[106:107], v[106:107], v[122:123]
	v_pk_mul_f32 v[104:105], v[104:105], v[120:121]
	s_nop 0
	v_cvt_pk_bf16_f32 v96, v104, v105
	v_cvt_pk_bf16_f32 v97, v106, v107
	v_cvt_pk_bf16_f32 v98, v98, v99
	v_cvt_pk_bf16_f32 v99, v100, v101
	v_mad_i64_i32 v[100:101], s[0:1], v102, s45, v[112:113]
	v_lshl_add_u64 v[100:101], v[100:101], 0, v[114:115]
	global_store_dwordx4 v[100:101], v[96:99], off
	s_nop 1
	v_mul_f32_e32 v96, 0xbfb8aa3b, v186
	v_pk_mul_f32 v[102:103], v[92:93], v[96:97] op_sel_hi:[1,0]
	v_pk_mul_f32 v[100:101], v[94:95], v[96:97] op_sel_hi:[1,0]
	v_exp_f32_e32 v97, v102
	v_exp_f32_e32 v99, v103
	v_exp_f32_e32 v102, v100
	v_exp_f32_e32 v103, v101
	v_add_f32_e32 v97, 1.0, v97
	v_rcp_f32_e32 v100, v97
	v_add_f32_e32 v97, 1.0, v99
	v_rcp_f32_e32 v101, v97
	v_add_f32_e32 v97, 1.0, v102
	v_rcp_f32_e32 v102, v97
	v_add_f32_e32 v97, 1.0, v103
	v_pk_mul_f32 v[92:93], v[86:87], v[96:97] op_sel_hi:[1,0]
	v_pk_mul_f32 v[94:95], v[84:85], v[96:97] op_sel_hi:[1,0]
	v_rcp_f32_e32 v103, v97
	v_exp_f32_e32 v94, v94
	v_exp_f32_e32 v95, v95
	v_exp_f32_e32 v96, v92
	v_exp_f32_e32 v97, v93
	v_add_f32_e32 v92, 1.0, v94
	v_add_f32_e32 v93, 1.0, v95
	v_add_f32_e32 v94, 1.0, v96
	v_add_f32_e32 v95, 1.0, v97
	v_rcp_f32_e32 v92, v92
	v_rcp_f32_e32 v93, v93
	v_rcp_f32_e32 v94, v94
	v_rcp_f32_e32 v95, v95
	v_mul_f32_e32 v98, v186, v186
	v_pk_mul_f32 v[80:81], v[80:81], v[98:99] op_sel_hi:[1,0]
	v_pk_mul_f32 v[82:83], v[82:83], v[98:99] op_sel_hi:[1,0]
	v_pk_mul_f32 v[88:89], v[88:89], v[98:99] op_sel_hi:[1,0]
	v_pk_mul_f32 v[90:91], v[90:91], v[98:99] op_sel_hi:[1,0]
	v_pk_mul_f32 v[84:85], v[82:83], v[94:95]
	v_pk_mul_f32 v[82:83], v[80:81], v[92:93]
	v_add_u32_e32 v86, 32, v181
	v_pk_mul_f32 v[90:91], v[90:91], v[102:103]
	v_pk_mul_f32 v[88:89], v[88:89], v[100:101]
	s_nop 0
	v_cvt_pk_bf16_f32 v80, v88, v89
	v_cvt_pk_bf16_f32 v81, v90, v91
	v_cvt_pk_bf16_f32 v82, v82, v83
	v_cvt_pk_bf16_f32 v83, v84, v85
	v_mad_i64_i32 v[84:85], s[0:1], v86, s45, v[112:113]
	v_lshl_add_u64 v[84:85], v[84:85], 0, v[114:115]
	global_store_dwordx4 v[84:85], v[80:83], off
	s_nop 1
	v_mul_f32_e32 v80, 0xbfb8aa3b, v234
	v_pk_mul_f32 v[86:87], v[76:77], v[80:81] op_sel_hi:[1,0]
	v_pk_mul_f32 v[84:85], v[78:79], v[80:81] op_sel_hi:[1,0]
	v_exp_f32_e32 v81, v86
	v_exp_f32_e32 v83, v87
	v_exp_f32_e32 v86, v84
	v_exp_f32_e32 v87, v85
	v_add_f32_e32 v81, 1.0, v81
	v_rcp_f32_e32 v84, v81
	v_add_f32_e32 v81, 1.0, v83
	v_rcp_f32_e32 v85, v81
	v_add_f32_e32 v81, 1.0, v86
	v_rcp_f32_e32 v86, v81
	v_add_f32_e32 v81, 1.0, v87
	v_pk_mul_f32 v[76:77], v[70:71], v[80:81] op_sel_hi:[1,0]
	v_pk_mul_f32 v[78:79], v[68:69], v[80:81] op_sel_hi:[1,0]
	v_rcp_f32_e32 v87, v81
	v_exp_f32_e32 v78, v78
	v_exp_f32_e32 v79, v79
	v_exp_f32_e32 v80, v76
	v_exp_f32_e32 v81, v77
	v_add_f32_e32 v76, 1.0, v78
	v_add_f32_e32 v77, 1.0, v79
	v_add_f32_e32 v78, 1.0, v80
	v_add_f32_e32 v79, 1.0, v81
	v_rcp_f32_e32 v76, v76
	v_rcp_f32_e32 v77, v77
	v_rcp_f32_e32 v78, v78
	v_rcp_f32_e32 v79, v79
	v_mul_f32_e32 v82, v234, v234
	v_pk_mul_f32 v[64:65], v[64:65], v[82:83] op_sel_hi:[1,0]
	v_pk_mul_f32 v[66:67], v[66:67], v[82:83] op_sel_hi:[1,0]
	v_pk_mul_f32 v[72:73], v[72:73], v[82:83] op_sel_hi:[1,0]
	v_pk_mul_f32 v[74:75], v[74:75], v[82:83] op_sel_hi:[1,0]
	v_pk_mul_f32 v[68:69], v[66:67], v[78:79]
	v_pk_mul_f32 v[66:67], v[64:65], v[76:77]
	v_add_u32_e32 v70, 48, v181
	v_pk_mul_f32 v[74:75], v[74:75], v[86:87]
	v_pk_mul_f32 v[72:73], v[72:73], v[84:85]
	s_nop 0
	v_cvt_pk_bf16_f32 v64, v72, v73
	v_cvt_pk_bf16_f32 v65, v74, v75
	v_cvt_pk_bf16_f32 v66, v66, v67
	v_cvt_pk_bf16_f32 v67, v68, v69
	v_mad_i64_i32 v[68:69], s[0:1], v70, s45, v[112:113]
	v_lshl_add_u64 v[68:69], v[68:69], 0, v[114:115]
	global_store_dwordx4 v[68:69], v[64:67], off
	s_nop 1
	v_add_u32_e32 v65, 0x80, v181
	v_mul_f32_e32 v64, 0xbfb8aa3b, v242
	v_pk_mul_f32 v[70:71], v[60:61], v[64:65] op_sel_hi:[1,0]
	v_pk_mul_f32 v[68:69], v[62:63], v[64:65] op_sel_hi:[1,0]
	v_exp_f32_e32 v67, v70
	v_exp_f32_e32 v70, v71
	v_exp_f32_e32 v71, v68
	v_exp_f32_e32 v72, v69
	v_add_f32_e32 v67, 1.0, v67
	v_rcp_f32_e32 v68, v67
	v_add_f32_e32 v67, 1.0, v70
	v_rcp_f32_e32 v69, v67
	v_add_f32_e32 v67, 1.0, v71
	v_mul_f32_e32 v66, v242, v242
	v_rcp_f32_e32 v70, v67
	v_add_f32_e32 v67, 1.0, v72
	v_pk_mul_f32 v[60:61], v[54:55], v[64:65] op_sel_hi:[1,0]
	v_pk_mul_f32 v[62:63], v[52:53], v[64:65] op_sel_hi:[1,0]
	v_rcp_f32_e32 v71, v67
	v_pk_mul_f32 v[56:57], v[56:57], v[66:67] op_sel_hi:[1,0]
	v_pk_mul_f32 v[58:59], v[58:59], v[66:67] op_sel_hi:[1,0]
	v_exp_f32_e32 v62, v62
	v_exp_f32_e32 v63, v63
	v_exp_f32_e32 v64, v60
	v_exp_f32_e32 v67, v61
	v_add_f32_e32 v60, 1.0, v62
	v_add_f32_e32 v61, 1.0, v63
	v_add_f32_e32 v62, 1.0, v64
	v_add_f32_e32 v63, 1.0, v67
	v_rcp_f32_e32 v60, v60
	v_rcp_f32_e32 v61, v61
	v_rcp_f32_e32 v62, v62
	v_rcp_f32_e32 v63, v63
	v_pk_mul_f32 v[48:49], v[48:49], v[66:67] op_sel_hi:[1,0]
	v_pk_mul_f32 v[50:51], v[50:51], v[66:67] op_sel_hi:[1,0]
	v_pk_mul_f32 v[58:59], v[58:59], v[70:71]
	v_pk_mul_f32 v[52:53], v[50:51], v[62:63]
	v_pk_mul_f32 v[50:51], v[48:49], v[60:61]
	v_pk_mul_f32 v[56:57], v[56:57], v[68:69]
	s_nop 0
	v_cvt_pk_bf16_f32 v48, v56, v57
	v_cvt_pk_bf16_f32 v49, v58, v59
	v_cvt_pk_bf16_f32 v50, v50, v51
	v_cvt_pk_bf16_f32 v51, v52, v53
	v_mad_i64_i32 v[52:53], s[0:1], v65, s45, v[112:113]
	v_lshl_add_u64 v[52:53], v[52:53], 0, v[114:115]
	global_store_dwordx4 v[52:53], v[48:51], off
	s_nop 1
	v_mul_f32_e32 v48, 0xbfb8aa3b, v131
	v_pk_mul_f32 v[54:55], v[44:45], v[48:49] op_sel_hi:[1,0]
	v_pk_mul_f32 v[52:53], v[46:47], v[48:49] op_sel_hi:[1,0]
	v_exp_f32_e32 v49, v54
	v_exp_f32_e32 v51, v55
	v_exp_f32_e32 v54, v52
	v_exp_f32_e32 v55, v53
	v_add_f32_e32 v49, 1.0, v49
	v_rcp_f32_e32 v52, v49
	v_add_f32_e32 v49, 1.0, v51
	v_rcp_f32_e32 v53, v49
	v_add_f32_e32 v49, 1.0, v54
	v_rcp_f32_e32 v54, v49
	v_add_f32_e32 v49, 1.0, v55
	v_pk_mul_f32 v[44:45], v[38:39], v[48:49] op_sel_hi:[1,0]
	v_pk_mul_f32 v[46:47], v[36:37], v[48:49] op_sel_hi:[1,0]
	v_rcp_f32_e32 v55, v49
	v_exp_f32_e32 v46, v46
	v_exp_f32_e32 v47, v47
	v_exp_f32_e32 v48, v44
	v_exp_f32_e32 v49, v45
	v_add_f32_e32 v44, 1.0, v46
	v_add_f32_e32 v45, 1.0, v47
	v_add_f32_e32 v46, 1.0, v48
	v_add_f32_e32 v47, 1.0, v49
	v_rcp_f32_e32 v44, v44
	v_rcp_f32_e32 v45, v45
	v_rcp_f32_e32 v46, v46
	v_rcp_f32_e32 v47, v47
	v_mul_f32_e32 v50, v131, v131
	v_pk_mul_f32 v[32:33], v[32:33], v[50:51] op_sel_hi:[1,0]
	v_pk_mul_f32 v[34:35], v[34:35], v[50:51] op_sel_hi:[1,0]
	v_pk_mul_f32 v[40:41], v[40:41], v[50:51] op_sel_hi:[1,0]
	v_pk_mul_f32 v[42:43], v[42:43], v[50:51] op_sel_hi:[1,0]
	v_pk_mul_f32 v[36:37], v[34:35], v[46:47]
	v_pk_mul_f32 v[34:35], v[32:33], v[44:45]
	v_add_u32_e32 v38, 0x90, v181
	v_pk_mul_f32 v[42:43], v[42:43], v[54:55]
	v_pk_mul_f32 v[40:41], v[40:41], v[52:53]
	s_nop 0
	v_cvt_pk_bf16_f32 v32, v40, v41
	v_cvt_pk_bf16_f32 v33, v42, v43
	v_cvt_pk_bf16_f32 v34, v34, v35
	v_cvt_pk_bf16_f32 v35, v36, v37
	v_mad_i64_i32 v[36:37], s[0:1], v38, s45, v[112:113]
	v_lshl_add_u64 v[36:37], v[36:37], 0, v[114:115]
	global_store_dwordx4 v[36:37], v[32:35], off
	s_nop 1
	v_mul_f32_e32 v32, 0xbfb8aa3b, v243
	v_pk_mul_f32 v[38:39], v[28:29], v[32:33] op_sel_hi:[1,0]
	v_pk_mul_f32 v[36:37], v[30:31], v[32:33] op_sel_hi:[1,0]
	v_exp_f32_e32 v33, v38
	v_exp_f32_e32 v35, v39
	v_exp_f32_e32 v38, v36
	v_exp_f32_e32 v39, v37
	v_add_f32_e32 v33, 1.0, v33
	v_rcp_f32_e32 v36, v33
	v_add_f32_e32 v33, 1.0, v35
	v_rcp_f32_e32 v37, v33
	v_add_f32_e32 v33, 1.0, v38
	v_rcp_f32_e32 v38, v33
	v_add_f32_e32 v33, 1.0, v39
	v_pk_mul_f32 v[28:29], v[22:23], v[32:33] op_sel_hi:[1,0]
	v_pk_mul_f32 v[30:31], v[20:21], v[32:33] op_sel_hi:[1,0]
	v_rcp_f32_e32 v39, v33
	v_exp_f32_e32 v30, v30
	v_exp_f32_e32 v31, v31
	v_exp_f32_e32 v32, v28
	v_exp_f32_e32 v33, v29
	v_add_f32_e32 v28, 1.0, v30
	v_add_f32_e32 v29, 1.0, v31
	v_add_f32_e32 v30, 1.0, v32
	v_add_f32_e32 v31, 1.0, v33
	v_rcp_f32_e32 v28, v28
	v_rcp_f32_e32 v29, v29
	v_rcp_f32_e32 v30, v30
	v_rcp_f32_e32 v31, v31
	v_mul_f32_e32 v34, v243, v243
	v_pk_mul_f32 v[16:17], v[16:17], v[34:35] op_sel_hi:[1,0]
	v_pk_mul_f32 v[18:19], v[18:19], v[34:35] op_sel_hi:[1,0]
	v_pk_mul_f32 v[24:25], v[24:25], v[34:35] op_sel_hi:[1,0]
	v_pk_mul_f32 v[26:27], v[26:27], v[34:35] op_sel_hi:[1,0]
	v_pk_mul_f32 v[20:21], v[18:19], v[30:31]
	v_pk_mul_f32 v[18:19], v[16:17], v[28:29]
	v_add_u32_e32 v22, 0xa0, v181
	v_pk_mul_f32 v[26:27], v[26:27], v[38:39]
	v_pk_mul_f32 v[24:25], v[24:25], v[36:37]
	s_nop 0
	v_cvt_pk_bf16_f32 v16, v24, v25
	v_cvt_pk_bf16_f32 v17, v26, v27
	v_cvt_pk_bf16_f32 v18, v18, v19
	v_cvt_pk_bf16_f32 v19, v20, v21
	v_mad_i64_i32 v[20:21], s[0:1], v22, s45, v[112:113]
	v_lshl_add_u64 v[20:21], v[20:21], 0, v[114:115]
	global_store_dwordx4 v[20:21], v[16:19], off
	s_nop 1
	v_mul_f32_e32 v16, 0xbfb8aa3b, v128
	v_pk_mul_f32 v[22:23], v[12:13], v[16:17] op_sel_hi:[1,0]
	v_pk_mul_f32 v[20:21], v[14:15], v[16:17] op_sel_hi:[1,0]
	v_exp_f32_e32 v17, v22
	v_exp_f32_e32 v19, v23
	v_exp_f32_e32 v22, v20
	v_exp_f32_e32 v23, v21
	v_add_f32_e32 v17, 1.0, v17
	v_rcp_f32_e32 v20, v17
	v_add_f32_e32 v17, 1.0, v19
	v_rcp_f32_e32 v21, v17
	v_add_f32_e32 v17, 1.0, v22
	v_rcp_f32_e32 v22, v17
	v_add_f32_e32 v17, 1.0, v23
	v_pk_mul_f32 v[12:13], v[6:7], v[16:17] op_sel_hi:[1,0]
	v_pk_mul_f32 v[14:15], v[4:5], v[16:17] op_sel_hi:[1,0]
	v_rcp_f32_e32 v23, v17
	v_exp_f32_e32 v14, v14
	v_exp_f32_e32 v15, v15
	v_exp_f32_e32 v16, v12
	v_exp_f32_e32 v17, v13
	v_add_f32_e32 v12, 1.0, v14
	v_add_f32_e32 v13, 1.0, v15
	v_add_f32_e32 v14, 1.0, v16
	v_add_f32_e32 v15, 1.0, v17
	v_rcp_f32_e32 v12, v12
	v_rcp_f32_e32 v13, v13
	v_rcp_f32_e32 v14, v14
	v_rcp_f32_e32 v15, v15
	v_mul_f32_e32 v18, v128, v128
	v_pk_mul_f32 v[0:1], v[0:1], v[18:19] op_sel_hi:[1,0]
	v_pk_mul_f32 v[2:3], v[2:3], v[18:19] op_sel_hi:[1,0]
	v_pk_mul_f32 v[8:9], v[8:9], v[18:19] op_sel_hi:[1,0]
	v_pk_mul_f32 v[10:11], v[10:11], v[18:19] op_sel_hi:[1,0]
	v_pk_mul_f32 v[4:5], v[2:3], v[14:15]
	v_pk_mul_f32 v[2:3], v[0:1], v[12:13]
	v_add_u32_e32 v6, 0xb0, v181
	v_pk_mul_f32 v[10:11], v[10:11], v[22:23]
	v_pk_mul_f32 v[8:9], v[8:9], v[20:21]
	s_nop 0
	v_cvt_pk_bf16_f32 v0, v8, v9
	v_cvt_pk_bf16_f32 v1, v10, v11
	v_cvt_pk_bf16_f32 v2, v2, v3
	v_cvt_pk_bf16_f32 v3, v4, v5
	v_mad_i64_i32 v[4:5], s[0:1], v6, s45, v[112:113]
	v_lshl_add_u64 v[4:5], v[4:5], 0, v[114:115]
	s_mov_b64 s[0:1], -1
	global_store_dwordx4 v[4:5], v[0:3], off
	s_cbranch_vccnz .LBB0_628
	s_andn2_b64 vcc, exec, s[8:9]
	s_cbranch_vccnz .LBB0_627
	s_barrier
	s_branch .LBB0_627
.LBB0_638:
	s_mov_b32 s98, -1
	s_waitcnt vmcnt(0)
	s_barrier

.LBB0_1367:
	s_or_b32 s99, s0, 0x100
	s_cmp_eq_u32 s99, s98
	s_cbranch_scc1 .Lsw_skip_b
	s_mov_b32 s98, s99
	v_mov_b32_e32 v128, v173
	v_mov_b32_e32 v129, v172
	s_lshl_b32 s0, s0, 8
	s_add_i32 s0, s0, s35
	v_lshlrev_b32_e32 v144, 3, v128
	v_add_u32_e32 v181, s0, v129
	v_ashrrev_i32_e32 v145, 31, v144
	v_lshlrev_b32_e32 v160, 5, v181
	v_lshl_add_u64 v[182:183], v[144:145], 2, s[76:77]
	v_lshl_add_u64 v[132:133], v[160:161], 2, v[182:183]
	v_add_u32_e32 v136, 0x200, v160
	v_mov_b32_e32 v137, v161
	global_load_dwordx4 v[128:131], v[132:133], off
	s_nop 0
	global_load_dwordx4 v[132:135], v[132:133], off offset:16
	v_lshl_add_u64 v[140:141], v[136:137], 2, v[182:183]
	global_load_dwordx4 v[136:139], v[140:141], off
	s_nop 0
	global_load_dwordx4 v[140:143], v[140:141], off offset:16
	v_and_b32_e32 v148, 64, v178
	s_lshl_b32 s0, s1, 7
	v_xor_b32_e32 v146, 16, v178
	v_add_u32_e32 v148, 64, v148
	s_or_b32 s0, s0, s36
	v_cmp_lt_i32_e32 vcc, v146, v148
	v_mov_b32_e32 v145, v161
	v_add_u32_e32 v170, s0, v144
	v_cndmask_b32_e32 v146, v178, v146, vcc
	v_add_u32_e32 v144, 0x400, v160
	v_mov_b32_e32 v147, v161
	v_mov_b32_e32 v187, v161
	v_lshlrev_b32_e32 v171, 2, v146
	v_add_u32_e32 v146, 0x600, v160
	v_add_u32_e32 v186, 0x1400, v160
	v_lshl_add_u64 v[144:145], v[144:145], 2, v[182:183]
	v_lshl_add_u64 v[146:147], v[146:147], 2, v[182:183]
	v_lshl_add_u64 v[212:213], v[186:187], 2, v[182:183]
	global_load_dwordx4 v[186:189], v[144:145], off
	global_load_dwordx4 v[190:193], v[144:145], off offset:16
	global_load_dwordx4 v[194:197], v[146:147], off
	global_load_dwordx4 v[198:201], v[146:147], off offset:16
	v_xor_b32_e32 v150, 32, v178
	v_cmp_lt_i32_e32 vcc, v150, v148
	v_mov_b32_e32 v149, v161
	v_mov_b32_e32 v151, v161
	v_cndmask_b32_e32 v148, v178, v150, vcc
	v_lshlrev_b32_e32 v185, 2, v148
	v_add_u32_e32 v148, 0x1000, v160
	v_add_u32_e32 v150, 0x1200, v160
	v_add_u32_e32 v160, 0x1600, v160
	v_lshl_add_u64 v[148:149], v[148:149], 2, v[182:183]
	v_lshl_add_u64 v[210:211], v[150:151], 2, v[182:183]
	global_load_dwordx4 v[220:223], v[148:149], off
	global_load_dwordx4 v[224:227], v[148:149], off offset:16
	global_load_dwordx4 v[228:231], v[210:211], off
	global_load_dwordx4 v[232:235], v[210:211], off offset:16
	global_load_dwordx4 v[236:239], v[212:213], off
	global_load_dwordx4 v[240:243], v[212:213], off offset:16
	v_pk_mul_f32 v[122:123], v[126:127], v[122:123]
	v_pk_mul_f32 v[120:121], v[124:125], v[120:121]
	v_pk_mul_f32 v[112:113], v[116:117], v[112:113]
	v_pk_mul_f32 v[114:115], v[118:119], v[114:115]
	v_pk_mul_f32 v[106:107], v[110:111], v[106:107]
	v_pk_mul_f32 v[104:105], v[108:109], v[104:105]
	v_pk_mul_f32 v[98:99], v[102:103], v[98:99]
	v_pk_mul_f32 v[96:97], v[100:101], v[96:97]
	v_pk_mul_f32 v[90:91], v[94:95], v[90:91]
	v_pk_mul_f32 v[88:89], v[92:93], v[88:89]
	v_pk_mul_f32 v[82:83], v[86:87], v[82:83]
	v_pk_mul_f32 v[80:81], v[84:85], v[80:81]
	v_pk_mul_f32 v[74:75], v[78:79], v[74:75]
	v_pk_mul_f32 v[72:73], v[76:77], v[72:73]
	v_pk_mul_f32 v[66:67], v[70:71], v[66:67]
	v_pk_mul_f32 v[64:65], v[68:69], v[64:65]
	v_pk_mul_f32 v[58:59], v[62:63], v[58:59]
	v_pk_mul_f32 v[56:57], v[60:61], v[56:57]
	v_pk_mul_f32 v[50:51], v[54:55], v[50:51]
	v_pk_mul_f32 v[48:49], v[52:53], v[48:49]
	v_pk_mul_f32 v[42:43], v[46:47], v[42:43]
	v_pk_mul_f32 v[40:41], v[44:45], v[40:41]
	v_pk_mul_f32 v[34:35], v[38:39], v[34:35]
	v_pk_mul_f32 v[32:33], v[36:37], v[32:33]
	v_pk_mul_f32 v[26:27], v[30:31], v[26:27]
	v_pk_mul_f32 v[24:25], v[28:29], v[24:25]
	v_pk_mul_f32 v[18:19], v[22:23], v[18:19]
	v_pk_mul_f32 v[16:17], v[20:21], v[16:17]
	v_pk_mul_f32 v[10:11], v[14:15], v[10:11]
	v_pk_mul_f32 v[8:9], v[12:13], v[8:9]
	v_pk_mul_f32 v[2:3], v[6:7], v[2:3]
	v_pk_mul_f32 v[0:1], v[4:5], v[0:1]
	s_waitcnt vmcnt(0)
	v_mov_b32_e32 v144, v128
	v_mov_b32_e32 v145, v132
	v_mov_b32_e32 v132, v129
	v_mov_b32_e32 v128, v130
	v_mov_b32_e32 v129, v134
	v_mov_b32_e32 v134, v131
	v_mov_b32_e32 v130, v136
	v_mov_b32_e32 v131, v140
	v_mov_b32_e32 v140, v137
	v_mov_b32_e32 v136, v138
	v_mov_b32_e32 v137, v142
	v_mov_b32_e32 v142, v139
	v_pk_add_f32 v[132:133], v[144:145], v[132:133]
	v_pk_add_f32 v[128:129], v[128:129], v[134:135]
	v_pk_add_f32 v[130:131], v[130:131], v[140:141]
	v_pk_add_f32 v[134:135], v[136:137], v[142:143]
	v_pk_add_f32 v[128:129], v[132:133], v[128:129]
	v_pk_add_f32 v[130:131], v[130:131], v[134:135]
	v_add_f32_e32 v128, v128, v129
	v_add_f32_e32 v129, v130, v131
	s_nop 0
	s_waitcnt lgkmcnt(0)
	v_mov_b32_e32 v130, v128
	v_mov_b32_e32 v253, v128
	s_nop 1
	v_permlane16_swap_b32_e32 v130, v253
	v_add_f32_e32 v130, v130, v253
	s_waitcnt lgkmcnt(0)
	v_mov_b32_e32 v131, v129
	v_mov_b32_e32 v253, v129
	s_nop 1
	v_permlane16_swap_b32_e32 v131, v253
	v_add_f32_e32 v131, v131, v253
	v_lshl_add_u64 v[128:129], v[160:161], 2, v[182:183]
	s_waitcnt lgkmcnt(0)
	v_mov_b32_e32 v132, v130
	v_mov_b32_e32 v253, v130
	s_nop 1
	v_permlane32_swap_b32_e32 v132, v253
	v_add_f32_e32 v130, v132, v253
	v_fmamk_f32 v130, v130, 0x3a000000, v179
	v_rsq_f32_e32 v202, v130
	s_waitcnt lgkmcnt(0)
	v_mov_b32_e32 v133, v131
	v_mov_b32_e32 v253, v131
	s_nop 1
	v_permlane32_swap_b32_e32 v133, v253
	v_add_f32_e32 v131, v133, v253
	v_fmamk_f32 v131, v131, 0x3a000000, v179
	v_rsq_f32_e32 v203, v131
	global_load_dwordx4 v[132:135], v[128:129], off
	s_nop 0
	global_load_dwordx4 v[128:131], v[128:129], off offset:16
	v_mov_b32_e32 v182, v186
	v_mov_b32_e32 v183, v190
	v_mov_b32_e32 v190, v187
	v_mov_b32_e32 v186, v188
	v_mov_b32_e32 v187, v192
	v_mov_b32_e32 v192, v189
	v_pk_add_f32 v[182:183], v[182:183], v[190:191]
	v_pk_add_f32 v[186:187], v[186:187], v[192:193]
	v_pk_add_f32 v[182:183], v[182:183], v[186:187]
	v_add_f32_e32 v182, v182, v183
	v_mov_b32_e32 v160, v202
	v_mov_b32_e32 v244, v202
	s_waitcnt lgkmcnt(0)
	v_mov_b32_e32 v183, v182
	v_mov_b32_e32 v253, v182
	s_nop 1
	v_permlane16_swap_b32_e32 v183, v253
	v_add_f32_e32 v182, v183, v253
	s_waitcnt lgkmcnt(0)
	v_mov_b32_e32 v183, v182
	v_mov_b32_e32 v253, v182
	s_nop 1
	v_permlane32_swap_b32_e32 v183, v253
	v_add_f32_e32 v182, v183, v253
	v_fmamk_f32 v182, v182, 0x3a000000, v179
	v_rsq_f32_e32 v204, v182
	v_mov_b32_e32 v186, v196
	v_mov_b32_e32 v187, v200
	v_mov_b32_e32 v182, v194
	v_mov_b32_e32 v183, v198
	v_mov_b32_e32 v198, v195
	v_mov_b32_e32 v200, v197
	v_pk_add_f32 v[182:183], v[182:183], v[198:199]
	v_pk_add_f32 v[186:187], v[186:187], v[200:201]
	v_pk_add_f32 v[182:183], v[182:183], v[186:187]
	v_add_f32_e32 v182, v182, v183
	v_mov_b32_e32 v188, v203
	v_mov_b32_e32 v245, v203
	s_waitcnt lgkmcnt(0)
	v_mov_b32_e32 v183, v182
	v_mov_b32_e32 v253, v182
	s_nop 1
	v_permlane16_swap_b32_e32 v183, v253
	v_add_f32_e32 v182, v183, v253
	s_waitcnt lgkmcnt(0)
	v_mov_b32_e32 v183, v182
	v_mov_b32_e32 v253, v182
	s_nop 1
	v_permlane32_swap_b32_e32 v183, v253
	v_add_f32_e32 v182, v183, v253
	v_fmamk_f32 v182, v182, 0x3a000000, v179
	v_rsq_f32_e32 v205, v182
	s_waitcnt vmcnt(7)
	v_mov_b32_e32 v186, v222
	s_waitcnt vmcnt(6)
	v_mov_b32_e32 v187, v226
	v_mov_b32_e32 v182, v220
	v_mov_b32_e32 v183, v224
	v_mov_b32_e32 v224, v221
	v_mov_b32_e32 v226, v223
	v_pk_add_f32 v[182:183], v[182:183], v[224:225]
	v_pk_add_f32 v[186:187], v[186:187], v[226:227]
	v_pk_add_f32 v[182:183], v[182:183], v[186:187]
	v_add_f32_e32 v182, v182, v183
	s_waitcnt lgkmcnt(0)
	v_mov_b32_e32 v183, v182
	v_mov_b32_e32 v253, v182
	s_nop 1
	v_permlane16_swap_b32_e32 v183, v253
	v_add_f32_e32 v182, v183, v253
	v_mov_b32_e32 v186, v204
	v_mov_b32_e32 v246, v204
	s_waitcnt lgkmcnt(0)
	v_mov_b32_e32 v183, v182
	v_mov_b32_e32 v253, v182
	s_nop 1
	v_permlane32_swap_b32_e32 v183, v253
	v_add_f32_e32 v182, v183, v253
	v_fmamk_f32 v182, v182, 0x3a000000, v179
	v_rsq_f32_e32 v206, v182
	s_waitcnt vmcnt(5)
	v_mov_b32_e32 v182, v228
	s_waitcnt vmcnt(4)
	v_mov_b32_e32 v183, v232
	v_mov_b32_e32 v232, v229
	v_mov_b32_e32 v228, v230
	v_mov_b32_e32 v229, v234
	v_mov_b32_e32 v234, v231
	v_pk_add_f32 v[232:233], v[182:183], v[232:233]
	v_pk_add_f32 v[234:235], v[228:229], v[234:235]
	v_pk_add_f32 v[232:233], v[232:233], v[234:235]
	v_add_f32_e32 v232, v232, v233
	s_waitcnt lgkmcnt(0)
	v_mov_b32_e32 v233, v232
	v_mov_b32_e32 v253, v232
	s_nop 1
	v_permlane16_swap_b32_e32 v233, v253
	v_add_f32_e32 v232, v233, v253
	s_waitcnt lgkmcnt(0)
	v_mov_b32_e32 v233, v232
	v_mov_b32_e32 v253, v232
	s_nop 1
	v_permlane32_swap_b32_e32 v233, v253
	v_add_f32_e32 v232, v233, v253
	v_fmamk_f32 v232, v232, 0x3a000000, v179
	v_rsq_f32_e32 v207, v232
	v_mov_b32_e32 v234, v205
	v_mov_b32_e32 v247, v205
	s_waitcnt vmcnt(3)
	v_mov_b32_e32 v232, v236
	s_waitcnt vmcnt(2)
	v_mov_b32_e32 v233, v240
	v_mov_b32_e32 v240, v237
	v_mov_b32_e32 v236, v238
	v_mov_b32_e32 v237, v242
	v_mov_b32_e32 v242, v239
	v_pk_add_f32 v[240:241], v[232:233], v[240:241]
	v_pk_add_f32 v[242:243], v[236:237], v[242:243]
	v_pk_add_f32 v[240:241], v[240:241], v[242:243]
	v_add_f32_e32 v240, v240, v241
	s_waitcnt lgkmcnt(0)
	v_mov_b32_e32 v241, v240
	v_mov_b32_e32 v253, v240
	s_nop 1
	v_permlane16_swap_b32_e32 v241, v253
	v_add_f32_e32 v240, v241, v253
	s_waitcnt lgkmcnt(0)
	v_mov_b32_e32 v241, v240
	v_mov_b32_e32 v253, v240
	s_nop 1
	v_permlane32_swap_b32_e32 v241, v253
	v_add_f32_e32 v240, v241, v253
	v_fmamk_f32 v240, v240, 0x3a000000, v179
	v_rsq_f32_e32 v208, v240
	v_mov_b32_e32 v242, v206
	v_mov_b32_e32 v248, v206
	s_waitcnt vmcnt(1)
	v_mov_b32_e32 v240, v132
	s_waitcnt vmcnt(0)
	v_mov_b32_e32 v241, v128
	v_mov_b32_e32 v128, v133
	v_mov_b32_e32 v132, v134
	v_mov_b32_e32 v133, v130
	v_mov_b32_e32 v130, v135
	v_pk_add_f32 v[128:129], v[240:241], v[128:129]
	v_pk_add_f32 v[130:131], v[132:133], v[130:131]
	v_pk_add_f32 v[128:129], v[128:129], v[130:131]
	v_add_f32_e32 v128, v128, v129
	v_mov_b32_e32 v131, v207
	v_mov_b32_e32 v249, v207
	s_waitcnt lgkmcnt(0)
	v_mov_b32_e32 v129, v128
	v_mov_b32_e32 v253, v128
	s_nop 1
	v_permlane16_swap_b32_e32 v129, v253
	v_add_f32_e32 v128, v129, v253
	s_waitcnt lgkmcnt(0)
	v_mov_b32_e32 v129, v128
	v_mov_b32_e32 v253, v128
	s_nop 1
	v_permlane32_swap_b32_e32 v129, v253
	v_add_f32_e32 v128, v129, v253
	v_fmamk_f32 v128, v128, 0x3a000000, v179
	v_rsq_f32_e32 v209, v128
	v_mov_b32_e32 v243, v208
	v_mov_b32_e32 v250, v208
	v_ashrrev_i32_e32 v171, 31, v170
	v_mul_f32_e32 v130, 0xbfb8aa3b, v160
	v_pk_mul_f32 v[240:241], v[124:125], v[130:131] op_sel_hi:[1,0]
	v_mov_b32_e32 v128, v209
	v_mov_b32_e32 v251, v209
	s_branch .Lsw_join_b
.Lsw_skip_b:
	v_mov_b32_e32 v128, v173
	v_mov_b32_e32 v129, v172
	s_lshl_b32 s0, s0, 8
	s_add_i32 s0, s0, s35
	v_lshlrev_b32_e32 v144, 3, v128
	v_add_u32_e32 v181, s0, v129
	v_ashrrev_i32_e32 v145, 31, v144
	v_lshlrev_b32_e32 v160, 5, v181
	v_lshl_add_u64 v[182:183], v[144:145], 2, s[76:77]
	v_lshl_add_u64 v[132:133], v[160:161], 2, v[182:183]
	v_add_u32_e32 v136, 0x200, v160
	v_mov_b32_e32 v137, v161
	v_lshl_add_u64 v[140:141], v[136:137], 2, v[182:183]
	v_and_b32_e32 v148, 64, v178
	s_lshl_b32 s0, s1, 7
	v_xor_b32_e32 v146, 16, v178
	v_add_u32_e32 v148, 64, v148
	s_or_b32 s0, s0, s36
	v_cmp_lt_i32_e32 vcc, v146, v148
	v_mov_b32_e32 v145, v161
	v_add_u32_e32 v170, s0, v144
	v_cndmask_b32_e32 v146, v178, v146, vcc
	v_add_u32_e32 v144, 0x400, v160
	v_mov_b32_e32 v147, v161
	v_mov_b32_e32 v187, v161
	v_lshlrev_b32_e32 v171, 2, v146
	v_add_u32_e32 v146, 0x600, v160
	v_add_u32_e32 v186, 0x1400, v160
	v_lshl_add_u64 v[144:145], v[144:145], 2, v[182:183]
	v_lshl_add_u64 v[146:147], v[146:147], 2, v[182:183]
	v_lshl_add_u64 v[212:213], v[186:187], 2, v[182:183]
	v_xor_b32_e32 v150, 32, v178
	v_cmp_lt_i32_e32 vcc, v150, v148
	v_mov_b32_e32 v149, v161
	v_mov_b32_e32 v151, v161
	v_cndmask_b32_e32 v148, v178, v150, vcc
	v_lshlrev_b32_e32 v185, 2, v148
	v_add_u32_e32 v148, 0x1000, v160
	v_add_u32_e32 v150, 0x1200, v160
	v_add_u32_e32 v160, 0x1600, v160
	v_lshl_add_u64 v[148:149], v[148:149], 2, v[182:183]
	v_lshl_add_u64 v[210:211], v[150:151], 2, v[182:183]
	v_pk_mul_f32 v[122:123], v[126:127], v[122:123]
	v_pk_mul_f32 v[120:121], v[124:125], v[120:121]
	v_pk_mul_f32 v[112:113], v[116:117], v[112:113]
	v_pk_mul_f32 v[114:115], v[118:119], v[114:115]
	v_pk_mul_f32 v[106:107], v[110:111], v[106:107]
	v_pk_mul_f32 v[104:105], v[108:109], v[104:105]
	v_pk_mul_f32 v[98:99], v[102:103], v[98:99]
	v_pk_mul_f32 v[96:97], v[100:101], v[96:97]
	v_pk_mul_f32 v[90:91], v[94:95], v[90:91]
	v_pk_mul_f32 v[88:89], v[92:93], v[88:89]
	v_pk_mul_f32 v[82:83], v[86:87], v[82:83]
	v_pk_mul_f32 v[80:81], v[84:85], v[80:81]
	v_pk_mul_f32 v[74:75], v[78:79], v[74:75]
	v_pk_mul_f32 v[72:73], v[76:77], v[72:73]
	v_pk_mul_f32 v[66:67], v[70:71], v[66:67]
	v_pk_mul_f32 v[64:65], v[68:69], v[64:65]
	v_pk_mul_f32 v[58:59], v[62:63], v[58:59]
	v_pk_mul_f32 v[56:57], v[60:61], v[56:57]
	v_pk_mul_f32 v[50:51], v[54:55], v[50:51]
	v_pk_mul_f32 v[48:49], v[52:53], v[48:49]
	v_pk_mul_f32 v[42:43], v[46:47], v[42:43]
	v_pk_mul_f32 v[40:41], v[44:45], v[40:41]
	v_pk_mul_f32 v[34:35], v[38:39], v[34:35]
	v_pk_mul_f32 v[32:33], v[36:37], v[32:33]
	v_pk_mul_f32 v[26:27], v[30:31], v[26:27]
	v_pk_mul_f32 v[24:25], v[28:29], v[24:25]
	v_pk_mul_f32 v[18:19], v[22:23], v[18:19]
	v_pk_mul_f32 v[16:17], v[20:21], v[16:17]
	v_pk_mul_f32 v[10:11], v[14:15], v[10:11]
	v_pk_mul_f32 v[8:9], v[12:13], v[8:9]
	v_pk_mul_f32 v[2:3], v[6:7], v[2:3]
	v_pk_mul_f32 v[0:1], v[4:5], v[0:1]
	v_lshl_add_u64 v[128:129], v[160:161], 2, v[182:183]
	v_mov_b32_e32 v160, v244
	v_mov_b32_e32 v188, v245
	v_mov_b32_e32 v186, v246
	v_mov_b32_e32 v234, v247
	v_mov_b32_e32 v242, v248
	v_mov_b32_e32 v131, v249
	v_mov_b32_e32 v243, v250
	v_ashrrev_i32_e32 v171, 31, v170
	v_mul_f32_e32 v130, 0xbfb8aa3b, v160
	v_pk_mul_f32 v[240:241], v[124:125], v[130:131] op_sel_hi:[1,0]
	v_mov_b32_e32 v128, v251
.Lsw_join_b:
	v_exp_f32_e32 v129, v240
	v_pk_mul_f32 v[134:135], v[126:127], v[130:131] op_sel_hi:[1,0]
	v_exp_f32_e32 v133, v241
	v_exp_f32_e32 v240, v134
	v_exp_f32_e32 v241, v135
	v_add_f32_e32 v129, 1.0, v129
	v_rcp_f32_e32 v134, v129
	v_add_f32_e32 v129, 1.0, v133
	v_rcp_f32_e32 v135, v129
	v_add_f32_e32 v129, 1.0, v240
	v_pk_mul_f32 v[126:127], v[116:117], v[130:131] op_sel_hi:[1,0]
	v_rcp_f32_e32 v240, v129
	v_add_f32_e32 v129, 1.0, v241
	v_pk_mul_f32 v[124:125], v[118:119], v[130:131] op_sel_hi:[1,0]
	v_exp_f32_e32 v126, v126
	v_exp_f32_e32 v127, v127
	v_rcp_f32_e32 v241, v129
	v_exp_f32_e32 v129, v124
	v_exp_f32_e32 v130, v125
	v_add_f32_e32 v124, 1.0, v126
	v_add_f32_e32 v125, 1.0, v127
	v_rcp_f32_e32 v124, v124
	v_rcp_f32_e32 v125, v125
	v_add_f32_e32 v126, 1.0, v129
	v_add_f32_e32 v127, 1.0, v130
	v_rcp_f32_e32 v126, v126
	v_rcp_f32_e32 v127, v127
	v_mul_f32_e32 v132, v160, v160
	v_pk_mul_f32 v[112:113], v[112:113], v[132:133] op_sel_hi:[1,0]
	v_pk_mul_f32 v[120:121], v[120:121], v[132:133] op_sel_hi:[1,0]
	v_pk_mul_f32 v[122:123], v[122:123], v[132:133] op_sel_hi:[1,0]
	v_pk_mul_f32 v[114:115], v[114:115], v[132:133] op_sel_hi:[1,0]
	v_pk_mul_f32 v[112:113], v[112:113], v[124:125]
	v_pk_mul_f32 v[122:123], v[122:123], v[240:241]
	v_pk_mul_f32 v[120:121], v[120:121], v[134:135]
	v_pk_mul_f32 v[114:115], v[114:115], v[126:127]
	v_cvt_pk_bf16_f32 v116, v120, v121
	v_cvt_pk_bf16_f32 v117, v122, v123
	v_cvt_pk_bf16_f32 v118, v112, v113
	v_mov_b64_e32 v[112:113], s[68:69]
	v_cvt_pk_bf16_f32 v119, v114, v115
	v_mad_i64_i32 v[120:121], s[0:1], v181, s44, v[112:113]
	v_lshlrev_b64 v[114:115], 1, v[170:171]
	v_lshl_add_u64 v[120:121], v[120:121], 0, v[114:115]
	global_store_dwordx4 v[120:121], v[116:119], off
	s_andn2_b64 vcc, exec, s[4:5]
	s_nop 0
	v_mul_f32_e32 v116, 0xbfb8aa3b, v188
	v_pk_mul_f32 v[122:123], v[108:109], v[116:117] op_sel_hi:[1,0]
	v_pk_mul_f32 v[120:121], v[110:111], v[116:117] op_sel_hi:[1,0]
	v_exp_f32_e32 v117, v122
	v_exp_f32_e32 v119, v123
	v_exp_f32_e32 v122, v120
	v_exp_f32_e32 v123, v121
	v_add_f32_e32 v117, 1.0, v117
	v_rcp_f32_e32 v120, v117
	v_add_f32_e32 v117, 1.0, v119
	v_rcp_f32_e32 v121, v117
	v_add_f32_e32 v117, 1.0, v122
	v_rcp_f32_e32 v122, v117
	v_add_f32_e32 v117, 1.0, v123
	v_pk_mul_f32 v[108:109], v[102:103], v[116:117] op_sel_hi:[1,0]
	v_pk_mul_f32 v[110:111], v[100:101], v[116:117] op_sel_hi:[1,0]
	v_rcp_f32_e32 v123, v117
	v_exp_f32_e32 v110, v110
	v_exp_f32_e32 v111, v111
	v_exp_f32_e32 v116, v108
	v_exp_f32_e32 v117, v109
	v_add_f32_e32 v108, 1.0, v110
	v_add_f32_e32 v109, 1.0, v111
	v_add_f32_e32 v110, 1.0, v116
	v_add_f32_e32 v111, 1.0, v117
	v_rcp_f32_e32 v108, v108
	v_rcp_f32_e32 v109, v109
	v_rcp_f32_e32 v110, v110
	v_rcp_f32_e32 v111, v111
	v_mul_f32_e32 v118, v188, v188
	v_pk_mul_f32 v[96:97], v[96:97], v[118:119] op_sel_hi:[1,0]
	v_pk_mul_f32 v[98:99], v[98:99], v[118:119] op_sel_hi:[1,0]
	v_pk_mul_f32 v[104:105], v[104:105], v[118:119] op_sel_hi:[1,0]
	v_pk_mul_f32 v[106:107], v[106:107], v[118:119] op_sel_hi:[1,0]
	v_pk_mul_f32 v[100:101], v[98:99], v[110:111]
	v_pk_mul_f32 v[98:99], v[96:97], v[108:109]
	v_add_u32_e32 v102, 16, v181
	v_pk_mul_f32 v[106:107], v[106:107], v[122:123]
	v_pk_mul_f32 v[104:105], v[104:105], v[120:121]
	s_nop 0
	v_cvt_pk_bf16_f32 v96, v104, v105
	v_cvt_pk_bf16_f32 v97, v106, v107
	v_cvt_pk_bf16_f32 v98, v98, v99
	v_cvt_pk_bf16_f32 v99, v100, v101
	v_mad_i64_i32 v[100:101], s[0:1], v102, s44, v[112:113]
	v_lshl_add_u64 v[100:101], v[100:101], 0, v[114:115]
	global_store_dwordx4 v[100:101], v[96:99], off
	s_nop 1
	v_mul_f32_e32 v96, 0xbfb8aa3b, v186
	v_pk_mul_f32 v[102:103], v[92:93], v[96:97] op_sel_hi:[1,0]
	v_pk_mul_f32 v[100:101], v[94:95], v[96:97] op_sel_hi:[1,0]
	v_exp_f32_e32 v97, v102
	v_exp_f32_e32 v99, v103
	v_exp_f32_e32 v102, v100
	v_exp_f32_e32 v103, v101
	v_add_f32_e32 v97, 1.0, v97
	v_rcp_f32_e32 v100, v97
	v_add_f32_e32 v97, 1.0, v99
	v_rcp_f32_e32 v101, v97
	v_add_f32_e32 v97, 1.0, v102
	v_rcp_f32_e32 v102, v97
	v_add_f32_e32 v97, 1.0, v103
	v_pk_mul_f32 v[92:93], v[86:87], v[96:97] op_sel_hi:[1,0]
	v_pk_mul_f32 v[94:95], v[84:85], v[96:97] op_sel_hi:[1,0]
	v_rcp_f32_e32 v103, v97
	v_exp_f32_e32 v94, v94
	v_exp_f32_e32 v95, v95
	v_exp_f32_e32 v96, v92
	v_exp_f32_e32 v97, v93
	v_add_f32_e32 v92, 1.0, v94
	v_add_f32_e32 v93, 1.0, v95
	v_add_f32_e32 v94, 1.0, v96
	v_add_f32_e32 v95, 1.0, v97
	v_rcp_f32_e32 v92, v92
	v_rcp_f32_e32 v93, v93
	v_rcp_f32_e32 v94, v94
	v_rcp_f32_e32 v95, v95
	v_mul_f32_e32 v98, v186, v186
	v_pk_mul_f32 v[80:81], v[80:81], v[98:99] op_sel_hi:[1,0]
	v_pk_mul_f32 v[82:83], v[82:83], v[98:99] op_sel_hi:[1,0]
	v_pk_mul_f32 v[88:89], v[88:89], v[98:99] op_sel_hi:[1,0]
	v_pk_mul_f32 v[90:91], v[90:91], v[98:99] op_sel_hi:[1,0]
	v_pk_mul_f32 v[84:85], v[82:83], v[94:95]
	v_pk_mul_f32 v[82:83], v[80:81], v[92:93]
	v_add_u32_e32 v86, 32, v181
	v_pk_mul_f32 v[90:91], v[90:91], v[102:103]
	v_pk_mul_f32 v[88:89], v[88:89], v[100:101]
	s_nop 0
	v_cvt_pk_bf16_f32 v80, v88, v89
	v_cvt_pk_bf16_f32 v81, v90, v91
	v_cvt_pk_bf16_f32 v82, v82, v83
	v_cvt_pk_bf16_f32 v83, v84, v85
	v_mad_i64_i32 v[84:85], s[0:1], v86, s44, v[112:113]
	v_lshl_add_u64 v[84:85], v[84:85], 0, v[114:115]
	global_store_dwordx4 v[84:85], v[80:83], off
	s_nop 1
	v_mul_f32_e32 v80, 0xbfb8aa3b, v234
	v_pk_mul_f32 v[86:87], v[76:77], v[80:81] op_sel_hi:[1,0]
	v_pk_mul_f32 v[84:85], v[78:79], v[80:81] op_sel_hi:[1,0]
	v_exp_f32_e32 v81, v86
	v_exp_f32_e32 v83, v87
	v_exp_f32_e32 v86, v84
	v_exp_f32_e32 v87, v85
	v_add_f32_e32 v81, 1.0, v81
	v_rcp_f32_e32 v84, v81
	v_add_f32_e32 v81, 1.0, v83
	v_rcp_f32_e32 v85, v81
	v_add_f32_e32 v81, 1.0, v86
	v_rcp_f32_e32 v86, v81
	v_add_f32_e32 v81, 1.0, v87
	v_pk_mul_f32 v[76:77], v[70:71], v[80:81] op_sel_hi:[1,0]
	v_pk_mul_f32 v[78:79], v[68:69], v[80:81] op_sel_hi:[1,0]
	v_rcp_f32_e32 v87, v81
	v_exp_f32_e32 v78, v78
	v_exp_f32_e32 v79, v79
	v_exp_f32_e32 v80, v76
	v_exp_f32_e32 v81, v77
	v_add_f32_e32 v76, 1.0, v78
	v_add_f32_e32 v77, 1.0, v79
	v_add_f32_e32 v78, 1.0, v80
	v_add_f32_e32 v79, 1.0, v81
	v_rcp_f32_e32 v76, v76
	v_rcp_f32_e32 v77, v77
	v_rcp_f32_e32 v78, v78
	v_rcp_f32_e32 v79, v79
	v_mul_f32_e32 v82, v234, v234
	v_pk_mul_f32 v[64:65], v[64:65], v[82:83] op_sel_hi:[1,0]
	v_pk_mul_f32 v[66:67], v[66:67], v[82:83] op_sel_hi:[1,0]
	v_pk_mul_f32 v[72:73], v[72:73], v[82:83] op_sel_hi:[1,0]
	v_pk_mul_f32 v[74:75], v[74:75], v[82:83] op_sel_hi:[1,0]
	v_pk_mul_f32 v[68:69], v[66:67], v[78:79]
	v_pk_mul_f32 v[66:67], v[64:65], v[76:77]
	v_add_u32_e32 v70, 48, v181
	v_pk_mul_f32 v[74:75], v[74:75], v[86:87]
	v_pk_mul_f32 v[72:73], v[72:73], v[84:85]
	s_nop 0
	v_cvt_pk_bf16_f32 v64, v72, v73
	v_cvt_pk_bf16_f32 v65, v74, v75
	v_cvt_pk_bf16_f32 v66, v66, v67
	v_cvt_pk_bf16_f32 v67, v68, v69
	v_mad_i64_i32 v[68:69], s[0:1], v70, s44, v[112:113]
	v_lshl_add_u64 v[68:69], v[68:69], 0, v[114:115]
	global_store_dwordx4 v[68:69], v[64:67], off
	s_nop 1
	v_add_u32_e32 v65, 0x80, v181
	v_mul_f32_e32 v64, 0xbfb8aa3b, v242
	v_pk_mul_f32 v[70:71], v[60:61], v[64:65] op_sel_hi:[1,0]
	v_pk_mul_f32 v[68:69], v[62:63], v[64:65] op_sel_hi:[1,0]
	v_exp_f32_e32 v67, v70
	v_exp_f32_e32 v70, v71
	v_exp_f32_e32 v71, v68
	v_exp_f32_e32 v72, v69
	v_add_f32_e32 v67, 1.0, v67
	v_rcp_f32_e32 v68, v67
	v_add_f32_e32 v67, 1.0, v70
	v_rcp_f32_e32 v69, v67
	v_add_f32_e32 v67, 1.0, v71
	v_mul_f32_e32 v66, v242, v242
	v_rcp_f32_e32 v70, v67
	v_add_f32_e32 v67, 1.0, v72
	v_pk_mul_f32 v[60:61], v[54:55], v[64:65] op_sel_hi:[1,0]
	v_pk_mul_f32 v[62:63], v[52:53], v[64:65] op_sel_hi:[1,0]
	v_rcp_f32_e32 v71, v67
	v_pk_mul_f32 v[56:57], v[56:57], v[66:67] op_sel_hi:[1,0]
	v_pk_mul_f32 v[58:59], v[58:59], v[66:67] op_sel_hi:[1,0]
	v_exp_f32_e32 v62, v62
	v_exp_f32_e32 v63, v63
	v_exp_f32_e32 v64, v60
	v_exp_f32_e32 v67, v61
	v_add_f32_e32 v60, 1.0, v62
	v_add_f32_e32 v61, 1.0, v63
	v_add_f32_e32 v62, 1.0, v64
	v_add_f32_e32 v63, 1.0, v67
	v_rcp_f32_e32 v60, v60
	v_rcp_f32_e32 v61, v61
	v_rcp_f32_e32 v62, v62
	v_rcp_f32_e32 v63, v63
	v_pk_mul_f32 v[48:49], v[48:49], v[66:67] op_sel_hi:[1,0]
	v_pk_mul_f32 v[50:51], v[50:51], v[66:67] op_sel_hi:[1,0]
	v_pk_mul_f32 v[58:59], v[58:59], v[70:71]
	v_pk_mul_f32 v[52:53], v[50:51], v[62:63]
	v_pk_mul_f32 v[50:51], v[48:49], v[60:61]
	v_pk_mul_f32 v[56:57], v[56:57], v[68:69]
	s_nop 0
	v_cvt_pk_bf16_f32 v48, v56, v57
	v_cvt_pk_bf16_f32 v49, v58, v59
	v_cvt_pk_bf16_f32 v50, v50, v51
	v_cvt_pk_bf16_f32 v51, v52, v53
	v_mad_i64_i32 v[52:53], s[0:1], v65, s44, v[112:113]
	v_lshl_add_u64 v[52:53], v[52:53], 0, v[114:115]
	global_store_dwordx4 v[52:53], v[48:51], off
	s_nop 1
	v_mul_f32_e32 v48, 0xbfb8aa3b, v131
	v_pk_mul_f32 v[54:55], v[44:45], v[48:49] op_sel_hi:[1,0]
	v_pk_mul_f32 v[52:53], v[46:47], v[48:49] op_sel_hi:[1,0]
	v_exp_f32_e32 v49, v54
	v_exp_f32_e32 v51, v55
	v_exp_f32_e32 v54, v52
	v_exp_f32_e32 v55, v53
	v_add_f32_e32 v49, 1.0, v49
	v_rcp_f32_e32 v52, v49
	v_add_f32_e32 v49, 1.0, v51
	v_rcp_f32_e32 v53, v49
	v_add_f32_e32 v49, 1.0, v54
	v_rcp_f32_e32 v54, v49
	v_add_f32_e32 v49, 1.0, v55
	v_pk_mul_f32 v[44:45], v[38:39], v[48:49] op_sel_hi:[1,0]
	v_pk_mul_f32 v[46:47], v[36:37], v[48:49] op_sel_hi:[1,0]
	v_rcp_f32_e32 v55, v49
	v_exp_f32_e32 v46, v46
	v_exp_f32_e32 v47, v47
	v_exp_f32_e32 v48, v44
	v_exp_f32_e32 v49, v45
	v_add_f32_e32 v44, 1.0, v46
	v_add_f32_e32 v45, 1.0, v47
	v_add_f32_e32 v46, 1.0, v48
	v_add_f32_e32 v47, 1.0, v49
	v_rcp_f32_e32 v44, v44
	v_rcp_f32_e32 v45, v45
	v_rcp_f32_e32 v46, v46
	v_rcp_f32_e32 v47, v47
	v_mul_f32_e32 v50, v131, v131
	v_pk_mul_f32 v[32:33], v[32:33], v[50:51] op_sel_hi:[1,0]
	v_pk_mul_f32 v[34:35], v[34:35], v[50:51] op_sel_hi:[1,0]
	v_pk_mul_f32 v[40:41], v[40:41], v[50:51] op_sel_hi:[1,0]
	v_pk_mul_f32 v[42:43], v[42:43], v[50:51] op_sel_hi:[1,0]
	v_pk_mul_f32 v[36:37], v[34:35], v[46:47]
	v_pk_mul_f32 v[34:35], v[32:33], v[44:45]
	v_add_u32_e32 v38, 0x90, v181
	v_pk_mul_f32 v[42:43], v[42:43], v[54:55]
	v_pk_mul_f32 v[40:41], v[40:41], v[52:53]
	s_nop 0
	v_cvt_pk_bf16_f32 v32, v40, v41
	v_cvt_pk_bf16_f32 v33, v42, v43
	v_cvt_pk_bf16_f32 v34, v34, v35
	v_cvt_pk_bf16_f32 v35, v36, v37
	v_mad_i64_i32 v[36:37], s[0:1], v38, s44, v[112:113]
	v_lshl_add_u64 v[36:37], v[36:37], 0, v[114:115]
	global_store_dwordx4 v[36:37], v[32:35], off
	s_nop 1
	v_mul_f32_e32 v32, 0xbfb8aa3b, v243
	v_pk_mul_f32 v[38:39], v[28:29], v[32:33] op_sel_hi:[1,0]
	v_pk_mul_f32 v[36:37], v[30:31], v[32:33] op_sel_hi:[1,0]
	v_exp_f32_e32 v33, v38
	v_exp_f32_e32 v35, v39
	v_exp_f32_e32 v38, v36
	v_exp_f32_e32 v39, v37
	v_add_f32_e32 v33, 1.0, v33
	v_rcp_f32_e32 v36, v33
	v_add_f32_e32 v33, 1.0, v35
	v_rcp_f32_e32 v37, v33
	v_add_f32_e32 v33, 1.0, v38
	v_rcp_f32_e32 v38, v33
	v_add_f32_e32 v33, 1.0, v39
	v_pk_mul_f32 v[28:29], v[22:23], v[32:33] op_sel_hi:[1,0]
	v_pk_mul_f32 v[30:31], v[20:21], v[32:33] op_sel_hi:[1,0]
	v_rcp_f32_e32 v39, v33
	v_exp_f32_e32 v30, v30
	v_exp_f32_e32 v31, v31
	v_exp_f32_e32 v32, v28
	v_exp_f32_e32 v33, v29
	v_add_f32_e32 v28, 1.0, v30
	v_add_f32_e32 v29, 1.0, v31
	v_add_f32_e32 v30, 1.0, v32
	v_add_f32_e32 v31, 1.0, v33
	v_rcp_f32_e32 v28, v28
	v_rcp_f32_e32 v29, v29
	v_rcp_f32_e32 v30, v30
	v_rcp_f32_e32 v31, v31
	v_mul_f32_e32 v34, v243, v243
	v_pk_mul_f32 v[16:17], v[16:17], v[34:35] op_sel_hi:[1,0]
	v_pk_mul_f32 v[18:19], v[18:19], v[34:35] op_sel_hi:[1,0]
	v_pk_mul_f32 v[24:25], v[24:25], v[34:35] op_sel_hi:[1,0]
	v_pk_mul_f32 v[26:27], v[26:27], v[34:35] op_sel_hi:[1,0]
	v_pk_mul_f32 v[20:21], v[18:19], v[30:31]
	v_pk_mul_f32 v[18:19], v[16:17], v[28:29]
	v_add_u32_e32 v22, 0xa0, v181
	v_pk_mul_f32 v[26:27], v[26:27], v[38:39]
	v_pk_mul_f32 v[24:25], v[24:25], v[36:37]
	s_nop 0
	v_cvt_pk_bf16_f32 v16, v24, v25
	v_cvt_pk_bf16_f32 v17, v26, v27
	v_cvt_pk_bf16_f32 v18, v18, v19
	v_cvt_pk_bf16_f32 v19, v20, v21
	v_mad_i64_i32 v[20:21], s[0:1], v22, s44, v[112:113]
	v_lshl_add_u64 v[20:21], v[20:21], 0, v[114:115]
	global_store_dwordx4 v[20:21], v[16:19], off
	s_nop 1
	v_mul_f32_e32 v16, 0xbfb8aa3b, v128
	v_pk_mul_f32 v[22:23], v[12:13], v[16:17] op_sel_hi:[1,0]
	v_pk_mul_f32 v[20:21], v[14:15], v[16:17] op_sel_hi:[1,0]
	v_exp_f32_e32 v17, v22
	v_exp_f32_e32 v19, v23
	v_exp_f32_e32 v22, v20
	v_exp_f32_e32 v23, v21
	v_add_f32_e32 v17, 1.0, v17
	v_rcp_f32_e32 v20, v17
	v_add_f32_e32 v17, 1.0, v19
	v_rcp_f32_e32 v21, v17
	v_add_f32_e32 v17, 1.0, v22
	v_rcp_f32_e32 v22, v17
	v_add_f32_e32 v17, 1.0, v23
	v_pk_mul_f32 v[12:13], v[6:7], v[16:17] op_sel_hi:[1,0]
	v_pk_mul_f32 v[14:15], v[4:5], v[16:17] op_sel_hi:[1,0]
	v_rcp_f32_e32 v23, v17
	v_exp_f32_e32 v14, v14
	v_exp_f32_e32 v15, v15
	v_exp_f32_e32 v16, v12
	v_exp_f32_e32 v17, v13
	v_add_f32_e32 v12, 1.0, v14
	v_add_f32_e32 v13, 1.0, v15
	v_add_f32_e32 v14, 1.0, v16
	v_add_f32_e32 v15, 1.0, v17
	v_rcp_f32_e32 v12, v12
	v_rcp_f32_e32 v13, v13
	v_rcp_f32_e32 v14, v14
	v_rcp_f32_e32 v15, v15
	v_mul_f32_e32 v18, v128, v128
	v_pk_mul_f32 v[0:1], v[0:1], v[18:19] op_sel_hi:[1,0]
	v_pk_mul_f32 v[2:3], v[2:3], v[18:19] op_sel_hi:[1,0]
	v_pk_mul_f32 v[8:9], v[8:9], v[18:19] op_sel_hi:[1,0]
	v_pk_mul_f32 v[10:11], v[10:11], v[18:19] op_sel_hi:[1,0]
	v_pk_mul_f32 v[4:5], v[2:3], v[14:15]
	v_pk_mul_f32 v[2:3], v[0:1], v[12:13]
	v_add_u32_e32 v6, 0xb0, v181
	v_pk_mul_f32 v[10:11], v[10:11], v[22:23]
	v_pk_mul_f32 v[8:9], v[8:9], v[20:21]
	s_nop 0
	v_cvt_pk_bf16_f32 v0, v8, v9
	v_cvt_pk_bf16_f32 v1, v10, v11
	v_cvt_pk_bf16_f32 v2, v2, v3
	v_cvt_pk_bf16_f32 v3, v4, v5
	v_mad_i64_i32 v[4:5], s[0:1], v6, s44, v[112:113]
	v_lshl_add_u64 v[4:5], v[4:5], 0, v[114:115]
	s_mov_b64 s[0:1], -1
	global_store_dwordx4 v[4:5], v[0:3], off
	s_cbranch_vccnz .LBB0_1360
	s_andn2_b64 vcc, exec, s[8:9]
	s_cbranch_vccnz .LBB0_1359
	s_barrier
	s_branch .LBB0_1359

	.amdhsa_kernel _Z8yoco_fwd6Params
		.amdhsa_group_segment_fixed_size 0
		.amdhsa_private_segment_fixed_size 0
		.amdhsa_kernarg_size 480
		.amdhsa_user_sgpr_count 2
		.amdhsa_user_sgpr_dispatch_ptr 0
		.amdhsa_user_sgpr_queue_ptr 0
		.amdhsa_user_sgpr_kernarg_segment_ptr 1
		.amdhsa_user_sgpr_dispatch_id 0
		.amdhsa_user_sgpr_kernarg_preload_length 0
		.amdhsa_user_sgpr_kernarg_preload_offset 0
		.amdhsa_user_sgpr_private_segment_size 0
		.amdhsa_uses_dynamic_stack 0
		.amdhsa_enable_private_segment 0
		.amdhsa_system_sgpr_workgroup_id_x 1
		.amdhsa_system_sgpr_workgroup_id_y 0
		.amdhsa_system_sgpr_workgroup_id_z 0
		.amdhsa_system_sgpr_workgroup_info 0
		.amdhsa_system_vgpr_workitem_id 2
		.amdhsa_next_free_vgpr 255
		.amdhsa_next_free_sgpr 100
		.amdhsa_accum_offset 256
		.amdhsa_reserve_vcc 1
		.amdhsa_float_round_mode_32 0
		.amdhsa_float_round_mode_16_64 0
		.amdhsa_float_denorm_mode_32 3
		.amdhsa_float_denorm_mode_16_64 3
		.amdhsa_dx10_clamp 1
		.amdhsa_ieee_mode 1
		.amdhsa_fp16_overflow 0
		.amdhsa_tg_split 0
		.amdhsa_exception_fp_ieee_invalid_op 0
		.amdhsa_exception_fp_denorm_src 0
		.amdhsa_exception_fp_ieee_div_zero 0
		.amdhsa_exception_fp_ieee_overflow 0
		.amdhsa_exception_fp_ieee_underflow 0
		.amdhsa_exception_fp_ieee_inexact 0
		.amdhsa_exception_int_div_zero 0
	.end_amdhsa_kernel

amdhsa.kernels:
  - .agpr_count:     0
    .args:
      - .offset:         0
        .size:           224
        .value_kind:     by_value
      - .offset:         224
        .size:           4
        .value_kind:     hidden_block_count_x
      - .offset:         228
        .size:           4
        .value_kind:     hidden_block_count_y
      - .offset:         232
        .size:           4
        .value_kind:     hidden_block_count_z
      - .offset:         236
        .size:           2
        .value_kind:     hidden_group_size_x
      - .offset:         238
        .size:           2
        .value_kind:     hidden_group_size_y
      - .offset:         240
        .size:           2
        .value_kind:     hidden_group_size_z
      - .offset:         242
        .size:           2
        .value_kind:     hidden_remainder_x
      - .offset:         244
        .size:           2
        .value_kind:     hidden_remainder_y
      - .offset:         246
        .size:           2
        .value_kind:     hidden_remainder_z
      - .offset:         264
        .size:           8
        .value_kind:     hidden_global_offset_x
      - .offset:         272
        .size:           8
        .value_kind:     hidden_global_offset_y
      - .offset:         280
        .size:           8
        .value_kind:     hidden_global_offset_z
      - .offset:         288
        .size:           2
        .value_kind:     hidden_grid_dims
      - .offset:         312
        .size:           8
        .value_kind:     hidden_multigrid_sync_arg
      - .offset:         344
        .size:           4
        .value_kind:     hidden_dynamic_lds_size
    .group_segment_fixed_size: 0
    .kernarg_segment_align: 8
    .kernarg_segment_size: 480
    .language:       OpenCL C
    .language_version:
      - 2
      - 0
    .max_flat_workgroup_size: 512
    .name:           _Z8yoco_fwd6Params
    .private_segment_fixed_size: 0
    .sgpr_count:     106
    .sgpr_spill_count: 52
    .symbol:         _Z8yoco_fwd6Params.kd
    .uniform_work_group_size: 1
    .uses_dynamic_stack: false
    .vgpr_count:     255
    .vgpr_spill_count: 0
    .wavefront_size: 64
